# grid barrier: XCD-last adds to every XCD generation word after write-back; all WGs spin with 4 polls in flight until (gen+1)*nx; top counter round trip removed
# baseline (speedup 1.0000x reference)
.LBB0_115:
	s_lshl_b32 s2, s86, 8
	s_add_u32 s4, s84, s2
	s_addc_u32 s5, s85, 0
	v_mov_b32_e32 v3, 0x1000
	v_mov_b32_e32 v5, 1
	global_atomic_add v5, v3, v5, s[4:5] offset:1024 sc0
	v_cvt_f32_u32_e32 v3, v4
	v_sub_u32_e32 v6, 0, v4
	v_rcp_iflag_f32_e32 v3, v3
	s_nop 0
	v_mul_f32_e32 v3, 0x4f7ffffe, v3
	v_cvt_u32_f32_e32 v3, v3
	v_mul_lo_u32 v6, v6, v3
	v_mul_hi_u32 v6, v3, v6
	v_add_u32_e32 v3, v3, v6
	s_waitcnt vmcnt(0)
	v_mul_hi_u32 v3, v5, v3
	v_mul_lo_u32 v6, v3, v4
	v_sub_u32_e32 v6, v5, v6
	v_add_u32_e32 v7, 1, v3
	v_cmp_ge_u32_e32 vcc, v6, v4
	v_add_u32_e32 v5, 1, v5
	s_nop 0
	v_cndmask_b32_e32 v3, v3, v7, vcc
	v_sub_u32_e32 v7, v6, v4
	v_cndmask_b32_e32 v6, v6, v7, vcc
	v_add_u32_e32 v7, 1, v3
	v_cmp_ge_u32_e32 vcc, v6, v4
	s_nop 1
	v_cndmask_b32_e32 v3, v3, v7, vcc
	v_mul_lo_u32 v6, v4, v3
	v_add_u32_e32 v4, v6, v4
	v_cmp_ne_u32_e32 vcc, v5, v4
	s_cbranch_vccnz .Lb3spin_0
	buffer_wbl2 sc1
	s_waitcnt vmcnt(0)
	v_mov_b32_e32 v6, 1
	v_mov_b32_e32 v7, 0x2400
	global_atomic_add v7, v6, s[84:85]
	v_mov_b32_e32 v17, 0x2500
	global_atomic_add v17, v6, s[84:85]
	v_mov_b32_e32 v7, 0x2600
	global_atomic_add v7, v6, s[84:85]
	v_mov_b32_e32 v17, 0x2700
	global_atomic_add v17, v6, s[84:85]
	v_mov_b32_e32 v7, 0x2800
	global_atomic_add v7, v6, s[84:85]
	v_mov_b32_e32 v17, 0x2900
	global_atomic_add v17, v6, s[84:85]
	v_mov_b32_e32 v7, 0x2a00
	global_atomic_add v7, v6, s[84:85]
	v_mov_b32_e32 v17, 0x2b00
	global_atomic_add v17, v6, s[84:85]
	v_mov_b32_e32 v7, 0x2c00
	global_atomic_add v7, v6, s[84:85]
	v_mov_b32_e32 v17, 0x2d00
	global_atomic_add v17, v6, s[84:85]
	v_mov_b32_e32 v7, 0x2e00
	global_atomic_add v7, v6, s[84:85]
	v_mov_b32_e32 v17, 0x2f00
	global_atomic_add v17, v6, s[84:85]
	v_mov_b32_e32 v7, 0x3000
	global_atomic_add v7, v6, s[84:85]
	v_mov_b32_e32 v17, 0x3100
	global_atomic_add v17, v6, s[84:85]
	v_mov_b32_e32 v7, 0x3200
	global_atomic_add v7, v6, s[84:85]
	v_mov_b32_e32 v17, 0x3300
	global_atomic_add v17, v6, s[84:85]
.Lb3spin_0:
	s_waitcnt lgkmcnt(0)
	v_add_u32_e32 v18, 1, v3
	v_mul_lo_u32 v18, v18, v2
	s_add_u32 s18, s4, 0x2400
	s_addc_u32 s19, s5, 0
	v_mov_b32_e32 v17, 0
	s_mov_b32 s20, 0
	global_load_dword v8, v17, s[18:19] sc1
	s_sleep 3
	global_load_dword v9, v17, s[18:19] sc1
	s_sleep 3
	global_load_dword v10, v17, s[18:19] sc1
	s_sleep 3
.Lb3loop_0:
	global_load_dword v11, v17, s[18:19] sc1
	s_waitcnt vmcnt(3)
	v_cmp_ge_u32_e32 vcc, v8, v18
	s_cbranch_vccnz .Lb3done_0
	s_sleep 3
	global_load_dword v8, v17, s[18:19] sc1
	s_waitcnt vmcnt(3)
	v_cmp_ge_u32_e32 vcc, v9, v18
	s_cbranch_vccnz .Lb3done_0
	s_sleep 3
	global_load_dword v9, v17, s[18:19] sc1
	s_waitcnt vmcnt(3)
	v_cmp_ge_u32_e32 vcc, v10, v18
	s_cbranch_vccnz .Lb3done_0
	s_sleep 3
	global_load_dword v10, v17, s[18:19] sc1
	s_waitcnt vmcnt(3)
	v_cmp_ge_u32_e32 vcc, v11, v18
	s_cbranch_vccnz .Lb3done_0
	s_sleep 3
	s_add_u32 s20, s20, 1
	s_cmp_lt_u32 s20, 0x200000
	s_cbranch_scc1 .Lb3loop_0
.Lb3done_0:
	s_waitcnt vmcnt(0)
	buffer_inv sc1
	s_waitcnt vmcnt(0)

.LBB0_645:
	s_lshl_b32 s2, s86, 8
	s_add_u32 s4, s84, s2
	s_addc_u32 s5, s85, 0
	v_mov_b32_e32 v2, 0x1000
	v_mov_b32_e32 v4, 1
	global_atomic_add v4, v2, v4, s[4:5] offset:1024 sc0
	v_cvt_f32_u32_e32 v2, v3
	v_sub_u32_e32 v5, 0, v3
	v_rcp_iflag_f32_e32 v2, v2
	s_nop 0
	v_mul_f32_e32 v2, 0x4f7ffffe, v2
	v_cvt_u32_f32_e32 v2, v2
	v_mul_lo_u32 v5, v5, v2
	v_mul_hi_u32 v5, v2, v5
	v_add_u32_e32 v2, v2, v5
	s_waitcnt vmcnt(0)
	v_mul_hi_u32 v2, v4, v2
	v_mul_lo_u32 v5, v2, v3
	v_sub_u32_e32 v5, v4, v5
	v_add_u32_e32 v6, 1, v2
	v_cmp_ge_u32_e32 vcc, v5, v3
	v_add_u32_e32 v4, 1, v4
	s_nop 0
	v_cndmask_b32_e32 v2, v2, v6, vcc
	v_sub_u32_e32 v6, v5, v3
	v_cndmask_b32_e32 v5, v5, v6, vcc
	v_add_u32_e32 v6, 1, v2
	v_cmp_ge_u32_e32 vcc, v5, v3
	s_nop 1
	v_cndmask_b32_e32 v2, v2, v6, vcc
	v_mul_lo_u32 v5, v3, v2
	v_add_u32_e32 v3, v5, v3
	v_cmp_ne_u32_e32 vcc, v4, v3
	s_cbranch_vccnz .Lb3spin_8
	buffer_wbl2 sc1
	s_waitcnt vmcnt(0)
	v_mov_b32_e32 v5, 1
	v_mov_b32_e32 v6, 0x2400
	global_atomic_add v6, v5, s[84:85]
	v_mov_b32_e32 v16, 0x2500
	global_atomic_add v16, v5, s[84:85]
	v_mov_b32_e32 v6, 0x2600
	global_atomic_add v6, v5, s[84:85]
	v_mov_b32_e32 v16, 0x2700
	global_atomic_add v16, v5, s[84:85]
	v_mov_b32_e32 v6, 0x2800
	global_atomic_add v6, v5, s[84:85]
	v_mov_b32_e32 v16, 0x2900
	global_atomic_add v16, v5, s[84:85]
	v_mov_b32_e32 v6, 0x2a00
	global_atomic_add v6, v5, s[84:85]
	v_mov_b32_e32 v16, 0x2b00
	global_atomic_add v16, v5, s[84:85]
	v_mov_b32_e32 v6, 0x2c00
	global_atomic_add v6, v5, s[84:85]
	v_mov_b32_e32 v16, 0x2d00
	global_atomic_add v16, v5, s[84:85]
	v_mov_b32_e32 v6, 0x2e00
	global_atomic_add v6, v5, s[84:85]
	v_mov_b32_e32 v16, 0x2f00
	global_atomic_add v16, v5, s[84:85]
	v_mov_b32_e32 v6, 0x3000
	global_atomic_add v6, v5, s[84:85]
	v_mov_b32_e32 v16, 0x3100
	global_atomic_add v16, v5, s[84:85]
	v_mov_b32_e32 v6, 0x3200
	global_atomic_add v6, v5, s[84:85]
	v_mov_b32_e32 v16, 0x3300
	global_atomic_add v16, v5, s[84:85]
.Lb3spin_8:
	s_waitcnt lgkmcnt(0)
	v_add_u32_e32 v17, 1, v2
	v_mul_lo_u32 v17, v17, v1
	s_add_u32 s18, s4, 0x2400
	s_addc_u32 s19, s5, 0
	v_mov_b32_e32 v16, 0
	s_mov_b32 s20, 0
	global_load_dword v7, v16, s[18:19] sc1
	s_sleep 3
	global_load_dword v8, v16, s[18:19] sc1
	s_sleep 3
	global_load_dword v9, v16, s[18:19] sc1
	s_sleep 3
.Lb3loop_8:
	global_load_dword v10, v16, s[18:19] sc1
	s_waitcnt vmcnt(3)
	v_cmp_ge_u32_e32 vcc, v7, v17
	s_cbranch_vccnz .Lb3done_8
	s_sleep 3
	global_load_dword v7, v16, s[18:19] sc1
	s_waitcnt vmcnt(3)
	v_cmp_ge_u32_e32 vcc, v8, v17
	s_cbranch_vccnz .Lb3done_8
	s_sleep 3
	global_load_dword v8, v16, s[18:19] sc1
	s_waitcnt vmcnt(3)
	v_cmp_ge_u32_e32 vcc, v9, v17
	s_cbranch_vccnz .Lb3done_8
	s_sleep 3
	global_load_dword v9, v16, s[18:19] sc1
	s_waitcnt vmcnt(3)
	v_cmp_ge_u32_e32 vcc, v10, v17
	s_cbranch_vccnz .Lb3done_8
	s_sleep 3
	s_add_u32 s20, s20, 1
	s_cmp_lt_u32 s20, 0x200000
	s_cbranch_scc1 .Lb3loop_8
